# next-layer wq/wkv gain weight conversion: 8 loads per inner iteration issued together with one wait (was 4 serialized round trips); on top of cumsum load fix
# speedup vs baseline: 1.0114x; 1.0012x over previous
; #define otid() otid_(wid_k)
; template <int MAP>
; DI void conv_weight(float* ldsf, const float* __restrict__ src, u16* __restrict__ dst, const float* __restrict__ gain, int K, int N, int Npad, int bid, int nblk, int wid_k) {
;   const int tid = otid(); const int tk = K >> 6; const int cnt = tk * (Npad >> 6);
;   for (int it = bid; it < cnt; it += nblk) {
;     const int kt = it % tk, nt = it / tk; const int k0 = kt * 64, n0 = nt * 64;
;     __syncthreads();
;     {
;       const int nn = tid & 63; int n = col_map<MAP>(n0 + nn); if (n >= N) n = -1;
; #pragma unroll 4
;       for (int r = 0; r < 8; ++r) {
;         const int kk = r * 8 + (tid >> 6);
;         float v = 0.f;
;         if (n >= 0) { v = __builtin_nontemporal_load(src + (size_t)(k0 + kk) * N + n); if (gain) v *= gain[k0 + kk]; }
;         ldsf[kk * 65 + nn] = v;
;       }
;     }
.LBB0_1403:
	v_mov_b32_e32 v10, 0
	v_mov_b32_e32 v16, 0
	v_mov_b32_e32 v17, 0
	v_mov_b32_e32 v19, 0
	v_lshl_add_u64 v[26:27], s[18:19], 0, v[8:9]
	s_and_saveexec_b64 s[20:21], vcc
	s_cbranch_execz .Lconvg1_skip
	v_add_u32_e32 v10, s24, v0
	v_ashrrev_i32_e32 v11, 31, v10
	v_mad_i64_i32 v[18:19], s[30:31], v10, s74, v[6:7]
	v_lshl_add_u64 v[10:11], v[10:11], 2, s[14:15]
	v_add3_u32 v20, v0, s24, 8
	v_mad_i64_i32 v[20:21], s[30:31], v20, s74, v[6:7]
	v_add3_u32 v22, v0, s24, 16
	v_mad_i64_i32 v[22:23], s[30:31], v22, s74, v[6:7]
	v_add3_u32 v24, v0, s24, 24
	v_mad_i64_i32 v[24:25], s[30:31], v24, s74, v[6:7]
	global_load_dword v18, v[18:19], off nt
	global_load_dword v10, v[10:11], off
	global_load_dword v20, v[20:21], off nt
	global_load_dword v21, v[26:27], off offset:-64
	global_load_dword v22, v[22:23], off nt
	global_load_dword v23, v[26:27], off offset:-32
	global_load_dword v24, v[24:25], off nt
	global_load_dword v25, v[26:27], off
	s_waitcnt vmcnt(0)
	v_mul_f32_e32 v10, v18, v10
	v_mul_f32_e32 v16, v20, v21
	v_mul_f32_e32 v17, v22, v23
	v_mul_f32_e32 v19, v24, v25
.Lconvg1_skip:
	s_or_b64 exec, exec, s[20:21]
	ds_write_b32 v5, v10
	ds_write_b32 v5, v16 offset:2080
	ds_write_b32 v5, v17 offset:4160
	ds_write_b32 v5, v19 offset:6240
	s_add_i32 s24, s24, 32
	s_add_u32 s18, s18, 0x80
	s_addc_u32 s19, s19, 0
	s_cmp_eq_u32 s24, 64
	v_add_u32_e32 v5, 0x2080, v5
	s_cbranch_scc0 .LBB0_1403
	s_branch .LBB0_1398

; #define otid() otid_(wid_k)
; template <int MAP>
; DI void conv_weight(float* ldsf, const float* __restrict__ src, u16* __restrict__ dst, const float* __restrict__ gain, int K, int N, int Npad, int bid, int nblk, int wid_k) {
;   const int tid = otid(); const int tk = K >> 6; const int cnt = tk * (Npad >> 6);
;   for (int it = bid; it < cnt; it += nblk) {
;     const int kt = it % tk, nt = it / tk; const int k0 = kt * 64, n0 = nt * 64;
;     __syncthreads();
;     {
;       const int nn = tid & 63; int n = col_map<MAP>(n0 + nn); if (n >= N) n = -1;
; #pragma unroll 4
;       for (int r = 0; r < 8; ++r) {
;         const int kk = r * 8 + (tid >> 6);
;         float v = 0.f;
;         if (n >= 0) { v = __builtin_nontemporal_load(src + (size_t)(k0 + kk) * N + n); if (gain) v *= gain[k0 + kk]; }
;         ldsf[kk * 65 + nn] = v;
;       }
;     }
.LBB0_1416:
	v_mov_b32_e32 v10, 0
	v_mov_b32_e32 v16, 0
	v_mov_b32_e32 v17, 0
	v_mov_b32_e32 v19, 0
	v_lshl_add_u64 v[26:27], s[22:23], 0, v[8:9]
	s_and_saveexec_b64 s[24:25], vcc
	s_cbranch_execz .Lconvg2_skip
	v_add_u32_e32 v10, s31, v0
	v_ashrrev_i32_e32 v11, 31, v10
	v_lshlrev_b64 v[18:19], 12, v[10:11]
	v_lshl_add_u64 v[18:19], v[6:7], 0, v[18:19]
	v_lshl_add_u64 v[10:11], v[10:11], 2, s[18:19]
	v_add3_u32 v20, v0, s31, 8
	v_ashrrev_i32_e32 v21, 31, v20
	v_lshlrev_b64 v[20:21], 12, v[20:21]
	v_lshl_add_u64 v[20:21], v[6:7], 0, v[20:21]
	v_add3_u32 v22, v0, s31, 16
	v_ashrrev_i32_e32 v23, 31, v22
	v_lshlrev_b64 v[22:23], 12, v[22:23]
	v_lshl_add_u64 v[22:23], v[6:7], 0, v[22:23]
	v_add3_u32 v24, v0, s31, 24
	v_ashrrev_i32_e32 v25, 31, v24
	v_lshlrev_b64 v[24:25], 12, v[24:25]
	v_lshl_add_u64 v[24:25], v[6:7], 0, v[24:25]
	global_load_dword v18, v[18:19], off nt
	global_load_dword v10, v[10:11], off
	global_load_dword v20, v[20:21], off nt
	global_load_dword v21, v[26:27], off offset:-64
	global_load_dword v22, v[22:23], off nt
	global_load_dword v23, v[26:27], off offset:-32
	global_load_dword v24, v[24:25], off nt
	global_load_dword v25, v[26:27], off
	s_waitcnt vmcnt(0)
	v_mul_f32_e32 v10, v18, v10
	v_mul_f32_e32 v16, v20, v21
	v_mul_f32_e32 v17, v22, v23
	v_mul_f32_e32 v19, v24, v25
.Lconvg2_skip:
	s_or_b64 exec, exec, s[24:25]
	ds_write_b32 v5, v10
	ds_write_b32 v5, v16 offset:2080
	ds_write_b32 v5, v17 offset:4160
	ds_write_b32 v5, v19 offset:6240
	s_add_i32 s31, s31, 32
	s_add_u32 s22, s22, 0x80
	s_addc_u32 s23, s23, 0
	s_cmp_eq_u32 s31, 64
	v_add_u32_e32 v5, 0x2080, v5
	s_cbranch_scc0 .LBB0_1416
	s_branch .LBB0_1413
